# grid barrier: follower workgroups poll the top-level generation word directly instead of the per-XCD generation word (one fewer relay hop per barrier), on top of permlane-swap hops
# baseline (speedup 1.0000x reference)
.LBB0_837:
	v_readlane_b32 s2, v254, 9
	v_readlane_b32 s3, v254, 10
	v_mov_b32_e32 v1, 1
	v_sub_u32_e32 v4, 0, v2
	s_nop 2
	global_atomic_add v3, v141, v1, s[2:3] sc0
	v_cvt_f32_u32_e32 v1, v2
	v_rcp_iflag_f32_e32 v1, v1
	s_nop 0
	v_mul_f32_e32 v1, 0x4f7ffffe, v1
	v_cvt_u32_f32_e32 v1, v1
	v_mul_lo_u32 v4, v4, v1
	v_mul_hi_u32 v4, v1, v4
	v_add_u32_e32 v1, v1, v4
	s_waitcnt vmcnt(0)
	v_mul_hi_u32 v1, v3, v1
	v_mul_lo_u32 v4, v1, v2
	v_sub_u32_e32 v4, v3, v4
	v_add_u32_e32 v5, 1, v1
	v_cmp_ge_u32_e32 vcc, v4, v2
	v_add_u32_e32 v3, 1, v3
	s_nop 0
	v_cndmask_b32_e32 v1, v1, v5, vcc
	v_sub_u32_e32 v5, v4, v2
	v_cndmask_b32_e32 v4, v4, v5, vcc
	v_add_u32_e32 v5, 1, v1
	v_cmp_ge_u32_e32 vcc, v4, v2
	s_nop 1
	v_cndmask_b32_e32 v1, v1, v5, vcc
	v_mul_lo_u32 v4, v2, v1
	v_add_u32_e32 v2, v4, v2
	v_cmp_ne_u32_e32 vcc, v3, v2
	s_and_saveexec_b64 s[6:7], vcc
	s_xor_b64 s[6:7], exec, s[6:7]
	s_cbranch_execz .LBB0_851
	v_readlane_b32 s2, v254, 15
	v_readlane_b32 s3, v254, 16
	s_waitcnt lgkmcnt(0)
	s_nop 3
	global_load_dword v0, v141, s[2:3] sc1
	s_waitcnt vmcnt(0)
	v_cmp_eq_u32_e32 vcc, v0, v1
	s_and_saveexec_b64 s[8:9], vcc
	s_cbranch_execz .LBB0_850
	s_mov_b32 s4, 1
	s_mov_b64 s[10:11], 0
	s_branch .LBB0_841

.LBB0_843:
	v_readlane_b32 s2, v254, 15
	v_readlane_b32 s3, v254, 16
	s_add_i32 s4, s4, 1
	s_mov_b64 s[16:17], -1
	s_nop 2
	global_load_dword v0, v141, s[2:3] sc1
	s_waitcnt vmcnt(0)
	v_cmp_ne_u32_e32 vcc, v0, v1
	s_orn2_b64 s[14:15], vcc, exec
	s_branch .LBB0_840
